# hg<true>: next-chunk loads use scalar base + invariant lane offsets (saddr) instead of per-chunk 64-bit VALU address math
# baseline (speedup 1.0000x reference)
; template <bool FULL, bool STORE = true>
; __device__ __forceinline__ void hg_item(const Prm& P, LAS unsigned char* lds, int item, int wave) {
;     ...
;     HG_LOADS(0);
.LBB0_838:
	s_or_b64 exec, exec, s[18:19]
	s_ashr_i32 s84, s91, 6
	s_and_b32 s18, s2, 7
	s_ashr_i32 s85, s84, 31
	s_lshl_b32 s33, s18, 21
	s_lshl_b32 s19, s54, 1
	s_lshl_b32 s87, s18, 10
	s_lshl_b64 s[52:53], s[84:85], 13
	s_lshl_b32 s18, s26, 10
	s_and_b32 s86, s19, 0x700
	s_or_b32 s18, s52, s18
	s_add_u32 s20, s18, s55
	v_lshlrev_b32_e32 v36, 1, v32
	s_addc_u32 s21, s53, 0
	s_lshl_b32 s22, s91, 4
	s_and_b32 s74, s22, 0x380
	v_ashrrev_i32_e32 v37, 31, v36
	v_lshl_add_u64 v[76:77], v[36:37], 0, s[74:75]
	v_lshlrev_b32_e32 v249, 1, v76
	v_add_u32_e32 v250, 0x1000, v249
	v_add_u32_e32 v251, 0x2000, v249
	v_add_u32_e32 v252, 0x3000, v249
	s_lshl_b64 s[20:21], s[20:21], 10
	v_lshl_add_u64 v[44:45], v[76:77], 0, s[20:21]
	v_lshlrev_b64 v[44:45], 1, v[44:45]
	v_lshl_add_u64 v[46:47], s[70:71], 0, v[44:45]
	global_load_dword v240, v[46:47], off nt
	v_lshl_add_u64 v[48:49], s[62:63], 0, v[44:45]
	global_load_dword v110, v[48:49], off nt
	v_lshl_add_u64 v[48:49], s[64:65], 0, v[44:45]
	s_mov_b64 s[20:21], 0x800
	v_ashrrev_i32_e32 v38, 3, v38
	s_mov_b32 s19, s53
	v_lshlrev_b32_e32 v43, 4, v32
	v_and_b32_e32 v94, 0x70, v43
	v_lshlrev_b32_e32 v74, 1, v94
	v_and_b32_e32 v60, 64, v108
	v_xor_b32_e32 v59, 1, v108
	v_add_u32_e32 v60, 64, v60
	v_cmp_lt_i32_e32 vcc, v59, v60
	v_lshlrev_b32_e32 v128, 4, v40
	v_readlane_b32 s46, v255, 48
	v_cndmask_b32_e32 v59, v108, v59, vcc
	v_lshlrev_b32_e32 v129, 2, v59
	v_xor_b32_e32 v59, 2, v108
	v_cmp_lt_i32_e32 vcc, v59, v60
	v_readlane_b32 s22, v255, 37
	v_readlane_b32 s24, v255, 38
	v_cndmask_b32_e32 v59, v108, v59, vcc
	v_lshlrev_b32_e32 v130, 2, v59
	v_xor_b32_e32 v59, 4, v108
	v_cmp_lt_i32_e32 vcc, v59, v60
	v_readlane_b32 s26, v255, 39
	v_readlane_b32 s28, v255, 40
	v_cndmask_b32_e32 v59, v108, v59, vcc
	v_readlane_b32 s30, v255, 41
	v_readlane_b32 s34, v255, 42
	v_readlane_b32 s36, v255, 43
	v_readlane_b32 s38, v255, 44
	v_readlane_b32 s40, v255, 45
	v_readlane_b32 s42, v255, 46
	v_readlane_b32 s44, v255, 47
	v_add_u32_e32 v96, s46, v34
	v_readlane_b32 s48, v255, 49
	v_readlane_b32 s50, v255, 50
	v_add_u32_e32 v61, s97, v34
	v_add_u32_e32 v63, s22, v34
	v_add_u32_e32 v64, s24, v34
	v_add_u32_e32 v65, s26, v34
	v_add_u32_e32 v66, s28, v34
	v_add_u32_e32 v67, s30, v34
	v_add_u32_e32 v68, s34, v34
	v_add_u32_e32 v69, s36, v34
	v_add_u32_e32 v70, s38, v34
	v_add_u32_e32 v71, s40, v34
	v_add_u32_e32 v72, s42, v34
	v_add_u32_e32 v73, s44, v34
	v_mul_lo_u32 v102, v96, s72
	v_lshlrev_b32_e32 v131, 2, v59
	v_or_b32_e32 v59, s97, v42
	v_lshlrev_b32_e32 v126, 3, v32
	v_mul_lo_u32 v58, v38, s94
	v_mul_u32_u24_e32 v41, 0x110, v33
	v_add_u32_e32 v58, 0, v58
	v_mad_u32_u24 v59, v59, s3, 0
	v_add_u32_e32 v133, v59, v128
	v_add_u32_e32 v156, v35, v41
	global_load_dword v111, v[48:49], off nt
	global_load_dword v241, v[46:47], off offset:2048 nt
	v_lshl_add_u64 v[46:47], v[44:45], 0, s[20:21]
	v_lshl_add_u64 v[48:49], s[62:63], 0, v[46:47]
	v_lshl_add_u64 v[46:47], s[64:65], 0, v[46:47]
	s_mov_b64 s[20:21], 0x1000
	global_load_dword v112, v[48:49], off nt
	global_load_dword v113, v[46:47], off nt
	v_lshl_add_u64 v[46:47], v[44:45], 0, s[20:21]
	v_lshl_add_u64 v[48:49], s[70:71], 0, v[46:47]
	s_mov_b64 s[20:21], 0x1800
	global_load_dword v242, v[48:49], off nt
	v_lshl_add_u64 v[48:49], s[62:63], 0, v[46:47]
	v_lshl_add_u64 v[46:47], s[64:65], 0, v[46:47]
	global_load_dword v114, v[48:49], off nt
	global_load_dword v115, v[46:47], off nt
	v_lshl_add_u64 v[46:47], v[44:45], 0, s[20:21]
	v_lshl_add_u64 v[48:49], s[70:71], 0, v[46:47]
	s_mov_b64 s[20:21], 0x2000
	global_load_dword v243, v[48:49], off nt
	v_lshl_add_u64 v[48:49], s[62:63], 0, v[46:47]
	v_lshl_add_u64 v[46:47], s[64:65], 0, v[46:47]
	global_load_dword v116, v[48:49], off nt
	global_load_dword v117, v[46:47], off nt
	v_lshl_add_u64 v[46:47], v[44:45], 0, s[20:21]
	v_lshl_add_u64 v[48:49], s[70:71], 0, v[46:47]
	s_mov_b64 s[20:21], 0x2800
	global_load_dword v244, v[48:49], off nt
	v_lshl_add_u64 v[48:49], s[62:63], 0, v[46:47]
	v_lshl_add_u64 v[46:47], s[64:65], 0, v[46:47]
	global_load_dword v118, v[48:49], off nt
	global_load_dword v119, v[46:47], off nt
	v_lshl_add_u64 v[46:47], v[44:45], 0, s[20:21]
	v_lshl_add_u64 v[48:49], s[70:71], 0, v[46:47]
	s_mov_b64 s[20:21], 0x3000
	global_load_dword v245, v[48:49], off nt
	v_lshl_add_u64 v[48:49], s[62:63], 0, v[46:47]
	v_lshl_add_u64 v[46:47], s[64:65], 0, v[46:47]
	global_load_dword v120, v[48:49], off nt
	global_load_dword v121, v[46:47], off nt
	v_lshl_add_u64 v[46:47], v[44:45], 0, s[20:21]
	v_lshl_add_u64 v[48:49], s[70:71], 0, v[46:47]
	s_mov_b64 s[20:21], 0x3800
	v_lshl_add_u64 v[44:45], v[44:45], 0, s[20:21]
	v_readlane_b32 s20, v255, 36
	global_load_dword v246, v[48:49], off nt
	v_lshl_add_u64 v[48:49], s[62:63], 0, v[46:47]
	v_lshl_add_u64 v[46:47], s[64:65], 0, v[46:47]
	global_load_dword v122, v[48:49], off nt
	global_load_dword v123, v[46:47], off nt
	v_lshl_add_u64 v[46:47], s[70:71], 0, v[44:45]
	v_add_u32_e32 v62, s20, v34
	global_load_dword v247, v[46:47], off nt
	v_lshl_add_u64 v[46:47], s[62:63], 0, v[44:45]
	v_lshl_add_u64 v[44:45], s[64:65], 0, v[44:45]
	global_load_dword v124, v[46:47], off nt
	global_load_dword v125, v[44:45], off nt
	v_lshlrev_b32_e32 v47, 2, v32
	v_ashrrev_i32_e32 v39, 31, v38
	v_lshl_add_u64 v[44:45], s[18:19], 0, v[38:39]
; #define LAS __attribute__((address_space(3)))
; __device__ __forceinline__ unsigned f2bf(float f) { unsigned u = __builtin_bit_cast(unsigned, f); return (u + 0x7fffu + ((u >> 16) & 1u)) >> 16; }
; template <bool FULL, bool STORE = true>
; __device__ __forceinline__ void hg_item(const Prm& P, LAS unsigned char* lds, int item, int wave) {
;     ...
;     HG_LOADS(0);
;     ...
;                 for (int r = 0; r < 16; ++r) { const int t = tb * 32 + (r & 3) + 8 * (r >> 2) + 4 * lh, s = sb * 32 + l31; *(LAS bf16_t*)(lds + HL_PP + t * 144 + s * 2) = (bf16_t)f2bf(s <= t ? sc[r] : 0.f); }
	v_lshlrev_b64 v[44:45], 11, v[44:45]
	v_lshl_add_u64 v[44:45], s[66:67], 0, v[44:45]
	s_lshl_b32 s18, s74, 1
	s_mov_b32 s19, s75
	v_lshl_add_u64 v[44:45], v[44:45], 0, s[18:19]
	v_lshl_add_u64 v[44:45], v[44:45], 0, v[74:75]
	global_load_dwordx4 v[48:51], v[44:45], off offset:16 nt
	global_load_dwordx4 v[52:55], v[44:45], off nt
	s_movk_i32 s18, 0x120
	v_mul_lo_u32 v127, v32, s18
	v_readlane_b32 s18, v255, 32
	s_add_i32 s19, 0, 0x15c00
	s_lshl_b32 s74, s74, 2
	v_or_b32_e32 v45, s18, v42
	s_add_i32 s18, 0, 0x11400
	v_mov_b32_e32 v40, s18
	v_add_u32_e32 v57, s18, v128
	v_readlane_b32 s18, v255, 34
	v_mov_b32_e32 v46, s19
	v_add_u32_e32 v74, s59, v34
	v_readlane_b32 s19, v255, 33
	v_or_b32_e32 v95, s18, v42
	v_or_b32_e32 v221, s97, v42
	v_mul_u32_u24_e32 v222, s72, v221
	v_add_lshl_u32 v223, v34, s18, 1
	v_add3_u32 v222, v222, v223, s73
	v_add_u32_e32 v221, s97, v221
	v_subrev_u32_e32 v221, s18, v221
	s_add_u32 vcc_lo, s82, s74
	v_mad_u32_u24 v40, v45, s72, v40
	v_mad_u32_u24 v45, v45, s3, v46
	v_lshl_add_u32 v46, v42, 2, s19
	v_readlane_b32 s19, v255, 29
	v_cmp_lt_i32_e64 s[46:47], v221, v96
	v_add_u32_e32 v96, s48, v34
	v_add_u32_e32 v34, s50, v34
	v_mul_lo_u32 v104, v74, s94
	v_lshlrev_b32_e32 v74, 2, v94
	s_addc_u32 vcc_hi, s83, 0
	v_or_b32_e32 v44, s59, v42
	v_or_b32_e32 v56, s19, v42
	v_mad_u32_u24 v60, v95, s3, 0
	v_lshl_add_u32 v42, v95, 1, s73
	v_cmp_lt_i32_e64 s[18:19], v221, v61
	v_cmp_lt_i32_e64 s[20:21], v221, v62
	v_cmp_lt_i32_e64 s[22:23], v221, v63
	v_cmp_lt_i32_e64 s[24:25], v221, v64
	v_cmp_lt_i32_e64 s[26:27], v221, v65
	v_cmp_lt_i32_e64 s[28:29], v221, v66
	v_cmp_lt_i32_e64 s[30:31], v221, v67
	v_cmp_lt_i32_e64 s[34:35], v221, v68
	v_cmp_lt_i32_e64 s[36:37], v221, v69
	v_cmp_lt_i32_e64 s[38:39], v221, v70
	v_cmp_lt_i32_e64 s[40:41], v221, v71
	v_cmp_lt_i32_e64 s[42:43], v221, v72
	v_cmp_lt_i32_e64 s[44:45], v221, v73
	v_cmp_lt_i32_e64 s[48:49], v221, v96
	v_cmp_lt_i32_e64 s[50:51], v221, v34
	v_lshl_add_u64 v[94:95], vcc, 0, v[74:75]
	s_lshl_b64 vcc, s[84:85], 24
	s_or_b32 vcc_lo, vcc_lo, s33
	v_readlane_b32 s33, v255, 55
	s_add_u32 s33, s33, s52
	s_addc_u32 s53, s90, s53
	v_lshlrev_b64 v[38:39], 11, v[38:39]
	v_and_b32_e32 v32, 7, v32
	s_add_u32 s52, s33, s87
	v_lshl_add_u64 v[38:39], vcc, 0, v[38:39]
	v_lshlrev_b32_e32 v32, 5, v32
	s_addc_u32 s53, s53, 0
	s_or_b32 s33, vcc_lo, s86
	v_mul_lo_u32 v43, v44, s72
	v_mul_lo_u32 v44, v44, s3
	v_mul_lo_u32 v56, v56, s72
	v_mul_lo_u32 v105, v34, s72
	v_mul_u32_u24_e32 v34, 0x90, v33
	v_or3_b32 v38, v38, s86, v32
	v_mov_b32_e32 v32, s33
	v_mov_b32_e32 v33, vcc_hi
	v_add_u32_e32 v43, s73, v43
	v_add_u32_e32 v44, 0, v44
	v_add_u32_e32 v56, 0, v56
	v_mul_lo_u32 v61, v61, s72
	v_mul_lo_u32 v62, v62, s72
	v_mul_lo_u32 v63, v63, s72
	v_mul_lo_u32 v64, v64, s72
	v_mul_lo_u32 v65, v65, s72
	v_mul_lo_u32 v66, v66, s72
	v_mul_lo_u32 v67, v67, s72
	v_mul_lo_u32 v68, v68, s72
	v_mul_lo_u32 v69, v69, s72
	v_mul_lo_u32 v70, v70, s72
	v_mul_lo_u32 v71, v71, s72
	v_mul_lo_u32 v72, v72, s72
	v_mul_lo_u32 v73, v73, s72
	v_mul_lo_u32 v103, v96, s72
	v_lshl_add_u64 v[32:33], v[36:37], 1, v[32:33]
	v_readlane_b32 s33, v255, 51
	v_mov_b32_e32 v253, v38
	v_lshl_add_u64 v[96:97], s[92:93], 0, v[38:39]
	s_lshl_b64 s[84:85], s[52:53], 10
	v_lshl_add_u64 v[98:99], s[78:79], 0, v[32:33]
	v_lshl_add_u64 v[100:101], s[80:81], 0, v[32:33]
	s_mov_b64 s[86:87], 0
	v_add_u32_e32 v132, s33, v47
	v_add_u32_e32 v134, v60, v128
	v_add_u32_e32 v135, v42, v61
	v_add_u32_e32 v136, v42, v62
	v_add_u32_e32 v137, v42, v63
	v_add_u32_e32 v138, v42, v64
	v_add_u32_e32 v139, v42, v65
	v_add_u32_e32 v140, v42, v66
	v_add_u32_e32 v141, v42, v67
	v_add_u32_e32 v142, v42, v68
	v_add_u32_e32 v143, v42, v69
	v_add_u32_e32 v144, v42, v70
	v_add_u32_e32 v145, v42, v71
	v_add_u32_e32 v146, v42, v72
	v_add_u32_e32 v147, v42, v73
	v_add_u32_e32 v148, v42, v102
	v_add_u32_e32 v149, v42, v103
	v_add_u32_e32 v150, v42, v105
	v_add_u32_e32 v151, v44, v128
	v_add_u32_e32 v152, v45, v128
	v_add_u32_e32 v153, v46, v104
	v_add_u32_e32 v154, v56, v128
	v_add_u32_e32 v155, v57, v34
	v_add_u32_e32 v157, v58, v74
	v_add_u32_e32 v158, v43, v128
	v_add_u32_e32 v159, v40, v128
	global_load_dwordx4 v[224:227], v[94:95], off offset:48
	global_load_dwordx4 v[228:231], v[94:95], off offset:32
	global_load_dwordx4 v[232:235], v[94:95], off offset:16
	global_load_dwordx4 v[236:239], v[94:95], off
	s_waitcnt vmcnt(8)
	v_cvt_f32_f16_e32 v78, v240
	v_cvt_f32_f16_sdwa v79, v240 dst_sel:DWORD dst_unused:UNUSED_PAD src0_sel:WORD_1
	v_cvt_f32_f16_e32 v80, v241
	v_cvt_f32_f16_sdwa v81, v241 dst_sel:DWORD dst_unused:UNUSED_PAD src0_sel:WORD_1
	v_cvt_f32_f16_e32 v82, v242
	v_cvt_f32_f16_sdwa v83, v242 dst_sel:DWORD dst_unused:UNUSED_PAD src0_sel:WORD_1
	v_cvt_f32_f16_e32 v84, v243
	v_cvt_f32_f16_sdwa v85, v243 dst_sel:DWORD dst_unused:UNUSED_PAD src0_sel:WORD_1
	v_cvt_f32_f16_e32 v86, v244
	v_cvt_f32_f16_sdwa v87, v244 dst_sel:DWORD dst_unused:UNUSED_PAD src0_sel:WORD_1
	v_cvt_f32_f16_e32 v88, v245
	v_cvt_f32_f16_sdwa v89, v245 dst_sel:DWORD dst_unused:UNUSED_PAD src0_sel:WORD_1
	v_cvt_f32_f16_e32 v90, v246
	v_cvt_f32_f16_sdwa v91, v246 dst_sel:DWORD dst_unused:UNUSED_PAD src0_sel:WORD_1
	v_cvt_f32_f16_e32 v92, v247
	v_cvt_f32_f16_sdwa v93, v247 dst_sel:DWORD dst_unused:UNUSED_PAD src0_sel:WORD_1
	s_branch .LBB0_840

; template <bool FULL, bool STORE = true>
; __device__ __forceinline__ void hg_item(const Prm& P, LAS unsigned char* lds, int item, int wave) {
;     ...
;         const u32x4 gcur0 = ghw0, gcur1 = ghw1;
;         if (ch + 1 < 16) HG_LOADS(ch + 1);
.LBB0_842:
	s_waitcnt vmcnt(1)
	v_mov_b64_e32 v[62:63], v[50:51]
	s_waitcnt vmcnt(0)
	v_mov_b64_e32 v[58:59], v[54:55]
	s_cmp_eq_u32 s86, 0x1e0000
	v_lshl_add_u64 v[102:103], v[96:97], 0, s[86:87]
	v_mov_b64_e32 v[60:61], v[48:49]
	v_mov_b64_e32 v[56:57], v[52:53]
	s_cbranch_scc1 .LBB0_844
	s_lshl_b64 s[52:53], s[84:85], 1
	s_add_u32 s32, s70, s52
	s_addc_u32 s33, s71, s53
	s_add_u32 s98, s62, s52
	s_addc_u32 s99, s63, s53
	s_add_u32 s52, s64, s52
	s_addc_u32 s53, s65, s53
	global_load_dword v240, v249, s[32:33] nt
	global_load_dword v110, v249, s[98:99] nt
	global_load_dword v111, v249, s[52:53] nt
	global_load_dword v241, v249, s[32:33] offset:2048 nt
	global_load_dword v112, v249, s[98:99] offset:2048 nt
	global_load_dword v113, v249, s[52:53] offset:2048 nt
	global_load_dword v242, v250, s[32:33] nt
	global_load_dword v114, v250, s[98:99] nt
	global_load_dword v115, v250, s[52:53] nt
	global_load_dword v243, v250, s[32:33] offset:2048 nt
	global_load_dword v116, v250, s[98:99] offset:2048 nt
	global_load_dword v117, v250, s[52:53] offset:2048 nt
	global_load_dword v244, v251, s[32:33] nt
	global_load_dword v118, v251, s[98:99] nt
	global_load_dword v119, v251, s[52:53] nt
	global_load_dword v245, v251, s[32:33] offset:2048 nt
	global_load_dword v120, v251, s[98:99] offset:2048 nt
	global_load_dword v121, v251, s[52:53] offset:2048 nt
	global_load_dword v246, v252, s[32:33] nt
	global_load_dword v122, v252, s[98:99] nt
	global_load_dword v123, v252, s[52:53] nt
	global_load_dword v247, v252, s[32:33] offset:2048 nt
	s_add_u32 s32, s92, s86
	s_addc_u32 s33, s93, s87
	s_add_u32 s32, s32, 0x13420000
	s_addc_u32 s33, s33, 0
	global_load_dwordx4 v[56:59], v253, s[32:33] nt
	global_load_dword v124, v252, s[98:99] offset:2048 nt
	global_load_dword v125, v252, s[52:53] offset:2048 nt
	global_load_dwordx4 v[60:63], v253, s[32:33] offset:16 nt

; __global__ void __launch_bounds__(NTHR, 2) fwd_megakernel(Prm P) {
	.amdhsa_kernel _Z14fwd_megakernel3Prm
		.amdhsa_group_segment_fixed_size 0
		.amdhsa_private_segment_fixed_size 0
		.amdhsa_kernarg_size 472
		.amdhsa_user_sgpr_count 2
		.amdhsa_user_sgpr_dispatch_ptr 0
		.amdhsa_user_sgpr_queue_ptr 0
		.amdhsa_user_sgpr_kernarg_segment_ptr 1
		.amdhsa_user_sgpr_dispatch_id 0
		.amdhsa_user_sgpr_kernarg_preload_length 0
		.amdhsa_user_sgpr_kernarg_preload_offset 0
		.amdhsa_user_sgpr_private_segment_size 0
		.amdhsa_uses_dynamic_stack 0
		.amdhsa_enable_private_segment 0
		.amdhsa_system_sgpr_workgroup_id_x 1
		.amdhsa_system_sgpr_workgroup_id_y 0
		.amdhsa_system_sgpr_workgroup_id_z 0
		.amdhsa_system_sgpr_workgroup_info 0
		.amdhsa_system_vgpr_workitem_id 2
		.amdhsa_next_free_vgpr 256
		.amdhsa_next_free_sgpr 100
		.amdhsa_accum_offset 256
		.amdhsa_reserve_vcc 1
		.amdhsa_float_round_mode_32 0
		.amdhsa_float_round_mode_16_64 0
		.amdhsa_float_denorm_mode_32 3
		.amdhsa_float_denorm_mode_16_64 3
		.amdhsa_dx10_clamp 1
		.amdhsa_ieee_mode 1
		.amdhsa_fp16_overflow 0
		.amdhsa_tg_split 0
		.amdhsa_exception_fp_ieee_invalid_op 0
		.amdhsa_exception_fp_denorm_src 0
		.amdhsa_exception_fp_ieee_div_zero 0
		.amdhsa_exception_fp_ieee_overflow 0
		.amdhsa_exception_fp_ieee_underflow 0
		.amdhsa_exception_fp_ieee_inexact 0
		.amdhsa_exception_int_div_zero 0
	.end_amdhsa_kernel

; __global__ void __launch_bounds__(NTHR, 2) fwd_megakernel(Prm P) {
amdhsa.kernels:
  - .agpr_count:     0
    .args:
      - .offset:         0
        .size:           216
        .value_kind:     by_value
      - .offset:         216
        .size:           4
        .value_kind:     hidden_block_count_x
      - .offset:         220
        .size:           4
        .value_kind:     hidden_block_count_y
      - .offset:         224
        .size:           4
        .value_kind:     hidden_block_count_z
      - .offset:         228
        .size:           2
        .value_kind:     hidden_group_size_x
      - .offset:         230
        .size:           2
        .value_kind:     hidden_group_size_y
      - .offset:         232
        .size:           2
        .value_kind:     hidden_group_size_z
      - .offset:         234
        .size:           2
        .value_kind:     hidden_remainder_x
      - .offset:         236
        .size:           2
        .value_kind:     hidden_remainder_y
      - .offset:         238
        .size:           2
        .value_kind:     hidden_remainder_z
      - .offset:         256
        .size:           8
        .value_kind:     hidden_global_offset_x
      - .offset:         264
        .size:           8
        .value_kind:     hidden_global_offset_y
      - .offset:         272
        .size:           8
        .value_kind:     hidden_global_offset_z
      - .offset:         280
        .size:           2
        .value_kind:     hidden_grid_dims
      - .offset:         304
        .size:           8
        .value_kind:     hidden_multigrid_sync_arg
      - .offset:         336
        .size:           4
        .value_kind:     hidden_dynamic_lds_size
    .group_segment_fixed_size: 0
    .kernarg_segment_align: 8
    .kernarg_segment_size: 472
    .language:       OpenCL C
    .language_version:
      - 2
      - 0
    .max_flat_workgroup_size: 512
    .name:           _Z14fwd_megakernel3Prm
    .private_segment_fixed_size: 0
    .sgpr_count:     106
    .sgpr_spill_count: 60
    .symbol:         _Z14fwd_megakernel3Prm.kd
    .uniform_work_group_size: 1
    .uses_dynamic_stack: false
    .vgpr_count:     256
    .vgpr_spill_count: 0
    .wavefront_size: 64
